# ret_kv arrival: returning add issued, XCC-last decision (write-back + global bump) deferred past the attention set-up; stale vmcnt waits in diff_ctx dropped
# speedup vs baseline: 1.0009x; 1.0009x over previous
.LBB0_384:
	s_cmp_lg_u32 s98, 0
	s_cbranch_scc0 .Lrk_noarr
	s_waitcnt vmcnt(0)
	s_barrier
	v_readlane_b32 s99, v254, 25
	v_readlane_b32 s100, v254, 24
	s_nop 3
	s_cmp_lg_u32 s99, 0
	s_cbranch_scc1 .Lrk_noarr
	s_lshl_b32 s100, s100, 8
	s_add_i32 s100, s100, 0xfa0c100
	v_mov_b32_e32 v0, s100
	v_mov_b32_e32 v1, 1
	s_mov_b64 s[100:101], exec
	s_mov_b64 exec, 1
	v_mov_b32_e32 v207, 0x21000
	ds_read_b32 v207, v207
	global_atomic_add v206, v0, v1, s[74:75] sc0

.Lrk_noarr:
	v_readlane_b32 s16, v254, 6
	v_readlane_b32 s17, v254, 7
	v_readlane_b32 s18, v254, 8
	v_readlane_b32 s19, v254, 9
	v_readlane_b32 s20, v254, 10
	v_readlane_b32 s21, v254, 11
	v_readlane_b32 s22, v254, 12
	v_readlane_b32 s23, v254, 13
	v_readlane_b32 s24, v254, 14
	v_readlane_b32 s25, v254, 15
	v_mbcnt_lo_u32_b32 v0, -1, 0
	v_mbcnt_hi_u32_b32 v0, -1, v0
	v_readlane_b32 s26, v254, 16
	v_ashrrev_i32_e32 v1, 31, v0
	v_readlane_b32 s27, v254, 17
	v_readlane_b32 s28, v254, 18
	v_readlane_b32 s29, v254, 19
	v_readlane_b32 s30, v254, 20
	v_readlane_b32 s31, v254, 21
	s_mov_b64 s[16:17], s[24:25]
	v_lshlrev_b64 v[0:1], 2, v[0:1]
	s_mov_b64 s[20:21], s[28:29]
	v_lshl_add_u64 v[2:3], s[20:21], 0, v[0:1]
	s_mov_b64 s[18:19], s[26:27]
	v_mov_b32_e32 v4, v200
	v_mov_b32_e32 v5, v201
	v_mov_b32_e32 v6, v202
	v_mov_b32_e32 v7, v203
	v_lshl_add_u64 v[2:3], s[16:17], 0, v[0:1]
	v_mov_b32_e32 v2, v204
	v_lshl_add_u64 v[0:1], s[18:19], 0, v[0:1]
	v_mov_b32_e32 v0, v205
	s_add_u32 s0, s74, 0xc600000
	v_writelane_b32 v255, s72, 0
	s_mov_b32 s1, 0xc2ce8ed0
	s_mov_b32 s2, 0x42b17218
	v_writelane_b32 v255, s73, 1
	v_writelane_b32 v255, s68, 2
	s_addc_u32 s3, s75, 0
	v_mov_b32_e32 v3, 0x7f800000
	v_writelane_b32 v255, s69, 3
	v_writelane_b32 v255, s0, 4
	s_mov_b32 s0, 0x3fb8aa3b
	v_writelane_b32 v255, s3, 5
	s_add_u32 s3, s74, 0xf900000
	v_writelane_b32 v255, s3, 6
	s_addc_u32 s3, s75, 0
	v_writelane_b32 v255, s3, 7
	s_add_u32 s3, s74, 0xfa04000
	v_writelane_b32 v255, s3, 8
	s_addc_u32 s3, s75, 0
	v_mov_b32_e32 v8, 0x3e4ccccd
	s_cmpk_lt_i32 s67, 0x100
	v_writelane_b32 v255, s3, 9
	v_writelane_b32 v255, s67, 10
	s_mov_b64 s[22:23], s[30:31]
	s_mov_b32 s9, 0
	v_mov_b32_e32 v1, 0
	s_mov_b64 s[4:5], -1
	s_movk_i32 s80, 0x1400
	s_mov_b64 s[34:35], 0x1000
	s_movk_i32 s81, 0xa00
	s_mov_b64 s[22:23], 0x100
	s_mov_b64 s[24:25], 0xa0000
	v_mov_b32_e32 v234, 0x358637bd
	s_nop 0
	v_mul_f32_e32 v9, v4, v5
	ds_swizzle_b32 v9, v9 offset:swizzle(SWAP,1)
	s_nop 0
	v_mul_f32_e32 v10, v6, v7
	ds_swizzle_b32 v10, v10 offset:swizzle(SWAP,1)
	s_nop 0
	v_and_b32_e32 v11, 0x7fffffff, v2
	ds_swizzle_b32 v11, v11 offset:swizzle(SWAP,1)
	s_nop 0
	v_and_b32_e32 v12, 0x7fffffff, v0
	ds_swizzle_b32 v12, v12 offset:swizzle(SWAP,1)
	s_waitcnt lgkmcnt(3)
	v_fmac_f32_e32 v9, v4, v5
	v_max_f32_e64 v2, |v2|, |v2|
	s_waitcnt lgkmcnt(2)
	v_fmac_f32_e32 v10, v6, v7
	s_waitcnt lgkmcnt(1)
	v_max_f32_e32 v4, v11, v11
	ds_swizzle_b32 v6, v9 offset:swizzle(SWAP,2)
	v_max_f32_e64 v0, |v0|, |v0|
	s_waitcnt lgkmcnt(1)
	v_max_f32_e32 v5, v12, v12
	ds_swizzle_b32 v7, v10 offset:swizzle(SWAP,2)
	v_max_f32_e32 v2, v2, v4
	v_max_f32_e32 v0, v0, v5
	ds_swizzle_b32 v4, v2 offset:swizzle(SWAP,2)
	ds_swizzle_b32 v5, v0 offset:swizzle(SWAP,2)
	s_waitcnt lgkmcnt(3)
	v_add_f32_e32 v6, v9, v6
	s_waitcnt lgkmcnt(2)
	v_add_f32_e32 v7, v10, v7
	ds_swizzle_b32 v9, v6 offset:swizzle(SWAP,4)
	ds_swizzle_b32 v10, v7 offset:swizzle(SWAP,4)
	s_waitcnt lgkmcnt(3)
	v_max_f32_e32 v4, v4, v4
	s_waitcnt lgkmcnt(2)
	v_max_f32_e32 v5, v5, v5
	v_max_f32_e32 v2, v2, v4
	v_max_f32_e32 v0, v0, v5
	ds_swizzle_b32 v4, v2 offset:swizzle(SWAP,4)
	ds_swizzle_b32 v5, v0 offset:swizzle(SWAP,4)
	s_waitcnt lgkmcnt(3)
	v_add_f32_e32 v6, v6, v9
	s_waitcnt lgkmcnt(2)
	v_add_f32_e32 v7, v7, v10
	ds_swizzle_b32 v9, v6 offset:swizzle(SWAP,8)
	ds_swizzle_b32 v10, v7 offset:swizzle(SWAP,8)
	s_waitcnt lgkmcnt(3)
	v_max_f32_e32 v4, v4, v4
	s_waitcnt lgkmcnt(2)
	v_max_f32_e32 v5, v5, v5
	v_max_f32_e32 v2, v2, v4
	v_max_f32_e32 v0, v0, v5
	ds_swizzle_b32 v4, v2 offset:swizzle(SWAP,8)
	ds_swizzle_b32 v5, v0 offset:swizzle(SWAP,8)
	s_waitcnt lgkmcnt(3)
	v_add_f32_e32 v6, v6, v9
	s_waitcnt lgkmcnt(2)
	v_add_f32_e32 v7, v7, v10
	ds_swizzle_b32 v9, v6 offset:swizzle(SWAP,16)
	ds_swizzle_b32 v10, v7 offset:swizzle(SWAP,16)
	s_waitcnt lgkmcnt(3)
	v_max_f32_e32 v4, v4, v4
	s_waitcnt lgkmcnt(2)
	v_max_f32_e32 v5, v5, v5
	v_max_f32_e32 v2, v2, v4
	v_max_f32_e32 v0, v0, v5
	ds_swizzle_b32 v4, v2 offset:swizzle(SWAP,16)
	s_waitcnt lgkmcnt(2)
	v_add_f32_e32 v6, v6, v9
	ds_swizzle_b32 v5, v0 offset:swizzle(SWAP,16)
	s_waitcnt lgkmcnt(2)
	v_add_f32_e32 v7, v7, v10
	v_mov_b32_e32 v9, v6
	v_mov_b32_e32 v10, v7
	s_nop 0
	v_permlane32_swap_b32_e32 v6, v9
	v_permlane32_swap_b32_e32 v7, v10
	v_add_f32_e32 v6, v6, v9
	v_add_f32_e32 v7, v7, v10
	v_mul_f32_e32 v9, 0x3fb8aa3b, v6
	v_mul_f32_e32 v10, 0x3fb8aa3b, v7
	s_waitcnt lgkmcnt(1)
	v_max_f32_e32 v4, v4, v4
	v_fma_f32 v11, v6, s0, -v9
	v_rndne_f32_e32 v12, v9
	s_waitcnt lgkmcnt(0)
	v_max_f32_e32 v5, v5, v5
	v_fma_f32 v13, v7, s0, -v10
	v_rndne_f32_e32 v14, v10
	v_max_f32_e32 v2, v2, v4
	v_fmac_f32_e32 v11, 0x32a5705f, v6
	v_sub_f32_e32 v4, v9, v12
	v_max_f32_e32 v0, v0, v5
	v_fmac_f32_e32 v13, 0x32a5705f, v7
	v_sub_f32_e32 v9, v10, v14
	v_add_f32_e32 v4, v4, v11
	v_cvt_i32_f32_e32 v5, v12
	v_cvt_i32_f32_e32 v10, v14
	v_mov_b32_e32 v12, v2
	v_mov_b32_e32 v14, v0
	v_add_f32_e32 v9, v9, v13
	v_exp_f32_e32 v4, v4
	v_permlane32_swap_b32_e32 v2, v12
	v_permlane32_swap_b32_e32 v0, v14
	v_exp_f32_e32 v9, v9
	v_max_f32_e32 v11, v12, v12
	v_max_f32_e32 v2, v2, v2
	v_max_f32_e32 v12, v14, v14
	v_max_f32_e32 v0, v0, v0
	v_max_f32_e32 v2, v2, v11
	v_max_f32_e32 v0, v0, v12
	v_mul_f32_e32 v0, v2, v0
	v_ldexp_f32 v2, v4, v5
	v_cmp_ngt_f32_e32 vcc, s1, v6
	v_ldexp_f32 v4, v9, v10
	v_mul_f32_e32 v0, 0x42800000, v0
	v_cndmask_b32_e32 v2, 0, v2, vcc
	v_cmp_ngt_f32_e32 vcc, s1, v7
	v_readlane_b32 s1, v254, 25
	s_mul_i32 s57, s1, 0xa000
	v_cndmask_b32_e32 v4, 0, v4, vcc
	v_cmp_nlt_f32_e32 vcc, s2, v6
	s_nop 1
	v_cndmask_b32_e32 v2, v3, v2, vcc
	v_cmp_nlt_f32_e32 vcc, s2, v7
	s_cselect_b64 s[2:3], -1, 0
	s_lshl_b32 s36, s1, 18
	v_cndmask_b32_e32 v3, v3, v4, vcc
	v_sub_f32_e32 v2, v2, v3
	s_or_b32 s54, s36, 0x10000
	v_readfirstlane_b32 s0, v2
	v_mov_b32_e32 v2, 0xc2700000
	v_fmac_f32_e32 v2, 0x3e38aa3b, v0
	v_add_f32_e32 v232, s0, v8
	s_lshl_b32 s0, s1, 12
	s_add_i32 s41, s0, 0
	s_lshl_b32 s0, s1, 13
	s_add_i32 s16, s0, 0
	s_add_i32 s0, s57, 0x7800
	v_writelane_b32 v255, s0, 11
	v_writelane_b32 v255, s2, 12
	s_mov_b32 s0, 0
	v_max_f32_e32 v0, 0, v2
	v_writelane_b32 v255, s3, 13
	v_writelane_b32 v255, s0, 14
	v_readfirstlane_b32 s40, v0
	s_cmp_lg_u32 s98, 0
	s_cbranch_scc0 .Lrk_late_end
	v_readlane_b32 s99, v254, 25
	s_nop 3
	s_cmp_lg_u32 s99, 0
	s_cbranch_scc1 .Lrk_late_end
	s_waitcnt vmcnt(0) lgkmcnt(0)
	v_readfirstlane_b32 s99, v206
	v_readfirstlane_b32 s100, v207
	s_add_i32 s99, s99, 1
	s_cmp_eq_u32 s99, s100
	s_cbranch_scc0 .Lrk_late_end
	buffer_wbl2 sc1
	s_waitcnt vmcnt(0)
	s_mov_b64 s[100:101], exec
	s_mov_b64 exec, 1
	v_mov_b32_e32 v206, 0xfa0e000
	v_mov_b32_e32 v207, 1
	global_atomic_add v206, v207, s[74:75]
	s_mov_b64 exec, s[100:101]
.Lrk_late_end:
	v_writelane_b32 v255, s78, 15
	s_or_b32 s55, s36, 0x20000
	v_cmp_neq_f32_e64 s[52:53], s40, 0
	s_or_b32 s56, s36, 0x30000
	s_add_i32 s58, s57, 0x2800
	s_add_i32 s59, s57, 0x5000
	v_cndmask_b32_e64 v233, 0, 1, s[2:3]
	s_add_i32 s19, s41, 0x8000
	s_add_i32 s43, s41, 0x400
	s_add_i32 s37, s41, 0x8400
	s_add_i32 s38, s41, 0x800
	s_add_i32 s39, s41, 0x8800
	s_add_i32 s42, s41, 0xc00
	s_add_i32 s66, s41, 0x8c00
	v_writelane_b32 v255, s79, 16
	s_branch .LBB0_386
